# sub-phase 3/4 job loops start at (bid&7)*32+(bid>>3): blocks of one XCD take 32 consecutive jobs per round (L2 reuse of shared operand tiles)
# speedup vs baseline: 1.0078x; 1.0010x over previous
.LBB0_230:
	v_readlane_b32 s0, v255, 18
	s_cmp_lt_i32 s0, 2
	s_mov_b64 s[0:1], -1
	s_cbranch_scc1 .LBB0_358
	v_readlane_b32 s0, v255, 18
	s_cmp_lt_i32 s0, 3
	s_mov_b64 s[0:1], -1
	s_cbranch_scc1 .LBB0_264
	v_readlane_b32 s0, v255, 18
	s_cmp_gt_i32 s0, 3
	s_mov_b64 s[0:1], -1
	s_cbranch_scc0 .LBB0_245
	s_cmpk_gt_i32 s74, 0x293
	s_cbranch_scc1 .LBB0_244
	s_and_b32 s98, s74, 7
	s_lshl_b32 s98, s98, 5
	s_lshr_b32 s99, s74, 3
	s_or_b32 s2, s98, s99
	s_branch .LBB0_237

.LBB0_245:
	s_andn2_b64 vcc, exec, s[0:1]
	s_cbranch_vccnz .LBB0_263
	s_cmpk_gt_i32 s74, 0x3df
	s_cbranch_scc1 .LBB0_263
	s_and_b32 s98, s74, 7
	s_lshl_b32 s98, s98, 5
	s_lshr_b32 s99, s74, 3
	s_or_b32 s6, s98, s99
	s_branch .LBB0_250
